# v6 + grid barrier leader path: XCD generation add issued before the leader's own acquire invalidate
# baseline (speedup 1.0000x reference)
.LBB0_331:
	s_or_b64 exec, exec, s[10:11]
	s_mov_b64 s[10:11], exec
	v_mbcnt_lo_u32_b32 v1, s10, 0
	v_mbcnt_hi_u32_b32 v1, s11, v1
	v_cmp_eq_u32_e32 vcc, 0, v1
	s_waitcnt vmcnt(0)
	s_and_saveexec_b64 s[12:13], vcc
	s_cbranch_execz .LBB0_333
	s_bcnt1_i32_b64 s10, s[10:11]
	v_mov_b32_e32 v1, 0x2000
	v_mov_b32_e32 v2, s10
	global_atomic_add v1, v2, s[8:9] offset:1024
.LBB0_333:
	s_or_b64 exec, exec, s[12:13]
	buffer_inv sc1
	s_waitcnt vmcnt(0)

.LBB0_1114:
	s_or_b64 exec, exec, s[6:7]
	s_mov_b64 s[6:7], exec
	v_mbcnt_lo_u32_b32 v1, s6, 0
	v_mbcnt_hi_u32_b32 v1, s7, v1
	v_cmp_eq_u32_e32 vcc, 0, v1
	s_waitcnt vmcnt(0)
	s_and_saveexec_b64 s[8:9], vcc
	s_cbranch_execz .LBB0_1116
	s_bcnt1_i32_b64 s6, s[6:7]
	v_mov_b32_e32 v1, 0x2000
	v_mov_b32_e32 v2, s6
	global_atomic_add v1, v2, s[4:5] offset:1024
.LBB0_1116:
	s_or_b64 exec, exec, s[8:9]
	buffer_inv sc1
	s_waitcnt vmcnt(0)

.LBB0_1386:
	s_or_b64 exec, exec, s[4:5]
	s_mov_b64 s[4:5], exec
	v_mbcnt_lo_u32_b32 v1, s4, 0
	v_mbcnt_hi_u32_b32 v1, s5, v1
	v_cmp_eq_u32_e32 vcc, 0, v1
	s_waitcnt vmcnt(0)
	s_and_saveexec_b64 s[6:7], vcc
	s_cbranch_execz .LBB0_1388
	s_bcnt1_i32_b64 s4, s[4:5]
	v_mov_b32_e32 v1, 0x2000
	v_mov_b32_e32 v2, s4
	global_atomic_add v1, v2, s[2:3] offset:1024
.LBB0_1388:
	s_or_b64 exec, exec, s[6:7]
	buffer_inv sc1
	s_waitcnt vmcnt(0)
